# attention: balanced MFMA gaps, one LDS refill per gap, load/store interleaved in step B1, q-gain table in LDS
# speedup vs baseline: 1.0295x; 1.0015x over previous
; __device__ __forceinline__ int opaque_tid() { int t = threadIdx.x; asm volatile("" : "+v"(t)); return t; }
; __device__ __forceinline__ void attn_phase(const Params& p, LAS unsigned char* lds, int G) {
;     ...
;     const int tid = opaque_tid(), lane = tid & 63, wave = __builtin_amdgcn_readfirstlane(tid >> 6), l32 = lane & 31, hi = lane >> 5;
;     const bf16_t* QRAW = (const bf16_t*)(ws + WS_QRAW); const bf16_t* KF = (const bf16_t*)(ws + WS_KF); const bf16_t* VT = (const bf16_t*)(ws + WS_VT);
;     const float* COS = (const float*)(ws + WS_COS); const float* SIN = (const float*)(ws + WS_SIN);
;     bf16_t* Y = (bf16_t*)(ws + WS_Y);
;     const int kr0 = tid / 12, kc0 = tid - kr0 * 12;
;     const int kr1 = (tid + 512) / 12, kc1 = (tid + 512) - kr1 * 12;
;     const int kr2 = (tid + 1024) / 12, kc2 = (tid + 1024) - kr2 * 12;
;     const int vr0 = tid >> 4, vc0 = tid & 15;
;     float negsb;
;     {
;         float gq = fmaxf(fabsf(p.in[15][lane]), fabsf(p.in[15][64 + l32])), gk = fmaxf(fabsf(p.in[16][lane]), fabsf(p.in[16][64 + l32]));
; #pragma unroll
;         for (int o = 1; o < 64; o <<= 1) { gq = fmaxf(gq, __shfl_xor(gq, o)); gk = fmaxf(gk, __shfl_xor(gk, o)); }
;         negsb = -(96.f * gq * gk * QSCALE);
;     }
;     f32x16 negv;
; #pragma unroll
;     for (int e = 0; e < 16; ++e) negv[e] = negsb;
;     asm volatile("" : "+v"(negv));
.LBB0_628:
	s_cmp_lt_i32 s94, 7
	s_cselect_b64 s[4:5], -1, 0
	s_and_b64 s[28:29], s[4:5], s[0:1]
	s_andn2_b64 vcc, exec, s[28:29]
	s_cbranch_vccnz .LBB0_660
	s_waitcnt vmcnt(0)
	v_mov_b32_e32 v16, v166
	v_mbcnt_lo_u32_b32 v4, -1, 0
	v_and_b32_e32 v17, 63, v16
	v_and_b32_e32 v170, 31, v16
	v_lshlrev_b32_e32 v0, 2, v17
	v_lshlrev_b32_e32 v171, 2, v170
	s_waitcnt lgkmcnt(0)
	global_load_dword v1, v171, s[70:71] offset:256
	global_load_dword v2, v0, s[70:71]
	global_load_dword v3, v171, s[72:73] offset:256
	s_nop 0
	global_load_dword v0, v0, s[72:73]
	v_mbcnt_hi_u32_b32 v4, -1, v4
	v_and_b32_e32 v5, 64, v4
	v_xor_b32_e32 v6, 1, v4
	v_add_u32_e32 v5, 64, v5
	v_cmp_lt_i32_e32 vcc, v6, v5
	v_xor_b32_e32 v7, 2, v4
	v_xor_b32_e32 v8, 4, v4
	v_cndmask_b32_e32 v6, v4, v6, vcc
	v_lshlrev_b32_e32 v167, 2, v6
	v_cmp_lt_i32_e32 vcc, v7, v5
	v_xor_b32_e32 v9, 8, v4
	v_xor_b32_e32 v10, 16, v4
	v_cndmask_b32_e32 v6, v4, v7, vcc
	v_lshlrev_b32_e32 v168, 2, v6
	v_cmp_lt_i32_e32 vcc, v8, v5
	v_xor_b32_e32 v11, 32, v4
	s_cmpk_gt_i32 s2, 0x7ff
	v_cndmask_b32_e32 v6, v4, v8, vcc
	v_lshlrev_b32_e32 v6, 2, v6
	v_cmp_lt_i32_e32 vcc, v9, v5
	s_mov_b32 s31, 0
	v_readfirstlane_b32 s0, v16
	s_waitcnt vmcnt(3)
	v_max_f32_e64 v1, |v1|, |v1|
	s_waitcnt vmcnt(2)
	v_max_f32_e64 v2, |v2|, |v2|
	s_waitcnt vmcnt(1)
	v_max_f32_e64 v3, |v3|, |v3|
	s_waitcnt vmcnt(0)
	v_max_f32_e64 v0, |v0|, |v0|
	v_max_f32_e32 v1, v2, v1
	v_max_f32_e32 v0, v0, v3
	ds_bpermute_b32 v2, v167, v1
	ds_bpermute_b32 v3, v167, v0
	s_waitcnt lgkmcnt(1)
	v_max_f32_e32 v2, v2, v2
	s_waitcnt lgkmcnt(0)
	v_max_f32_e32 v3, v3, v3
	v_max_f32_e32 v1, v1, v2
	v_max_f32_e32 v0, v0, v3
	ds_bpermute_b32 v2, v168, v1
	ds_bpermute_b32 v3, v168, v0
	s_waitcnt lgkmcnt(1)
	v_max_f32_e32 v2, v2, v2
	s_waitcnt lgkmcnt(0)
	v_max_f32_e32 v3, v3, v3
	v_max_f32_e32 v1, v1, v2
	v_max_f32_e32 v0, v0, v3
	ds_bpermute_b32 v2, v6, v1
	ds_bpermute_b32 v3, v6, v0
	v_cndmask_b32_e32 v6, v4, v9, vcc
	v_lshlrev_b32_e32 v6, 2, v6
	v_cmp_lt_i32_e32 vcc, v10, v5
	s_waitcnt lgkmcnt(1)
	v_max_f32_e32 v2, v2, v2
	s_waitcnt lgkmcnt(0)
	v_max_f32_e32 v3, v3, v3
	v_max_f32_e32 v1, v1, v2
	v_max_f32_e32 v0, v0, v3
	ds_bpermute_b32 v2, v6, v1
	ds_bpermute_b32 v3, v6, v0
	v_cndmask_b32_e32 v6, v4, v10, vcc
	v_lshlrev_b32_e32 v6, 2, v6
	v_cmp_lt_i32_e32 vcc, v11, v5
	s_waitcnt lgkmcnt(1)
	v_max_f32_e32 v2, v2, v2
	s_waitcnt lgkmcnt(0)
	v_max_f32_e32 v3, v3, v3
	v_max_f32_e32 v1, v1, v2
	v_max_f32_e32 v0, v0, v3
	ds_bpermute_b32 v2, v6, v1
	ds_bpermute_b32 v3, v6, v0
	v_cndmask_b32_e32 v4, v4, v11, vcc
	v_lshlrev_b32_e32 v169, 2, v4
	s_waitcnt lgkmcnt(1)
	v_max_f32_e32 v2, v2, v2
	s_waitcnt lgkmcnt(0)
	v_max_f32_e32 v3, v3, v3
	v_max_f32_e32 v1, v1, v2
	v_max_f32_e32 v0, v0, v3
	ds_bpermute_b32 v2, v169, v1
	ds_bpermute_b32 v3, v169, v0
	s_waitcnt lgkmcnt(1)
	v_max_f32_e32 v2, v2, v2
	s_waitcnt lgkmcnt(0)
	v_max_f32_e32 v3, v3, v3
	v_max_f32_e32 v1, v1, v2
	v_max_f32_e32 v0, v0, v3
	v_mul_f32_e32 v1, 0x42c00000, v1
	v_mul_f32_e32 v0, v0, v1
	v_mul_f32_e32 v0, 0xbe16c740, v0
	v_mov_b32_e32 v1, v0
	v_mov_b32_e32 v2, v0
	v_mov_b32_e32 v3, v0
	v_mov_b32_e32 v4, v0
	v_mov_b32_e32 v5, v0
	v_mov_b32_e32 v6, v0
	v_mov_b32_e32 v7, v0
	v_mov_b32_e32 v8, v0
	v_mov_b32_e32 v9, v0
	v_mov_b32_e32 v10, v0
	v_mov_b32_e32 v11, v0
	v_mov_b32_e32 v12, v0
	v_mov_b32_e32 v13, v0
	v_mov_b32_e32 v14, v0
	v_mov_b32_e32 v15, v0
	s_cbranch_scc1 .LBB0_649
; __device__ __forceinline__ void attn_phase(const Params& p, LAS unsigned char* lds, int G) {
;     ...
;     const bf16_t* QRAW = (const bf16_t*)(ws + WS_QRAW); const bf16_t* KF = (const bf16_t*)(ws + WS_KF); const bf16_t* VT = (const bf16_t*)(ws + WS_VT);
;     const float* COS = (const float*)(ws + WS_COS); const float* SIN = (const float*)(ws + WS_SIN);
;     bf16_t* Y = (bf16_t*)(ws + WS_Y);
;     const int kr0 = tid / 12, kc0 = tid - kr0 * 12;
;     const int kr1 = (tid + 512) / 12, kc1 = (tid + 512) - kr1 * 12;
;     const int kr2 = (tid + 1024) / 12, kc2 = (tid + 1024) - kr2 * 12;
;     const int vr0 = tid >> 4, vc0 = tid & 15;
;     ...
;             for (int ks = 0; ks < 6; ++ks) { const f32x4 ga = *(const f32x4*)(p.in[15] + 16 * ks + 8 * hi), gb = *(const f32x4*)(p.in[15] + 16 * ks + 8 * hi + 4);
;                 xa[ks] = xa[ks] * ga * r; xb[ks] = xb[ks] * gb * r; }
	v_add_u32_e32 v18, 0x200, v16
	s_mov_b32 s1, 0x2aaaaaab
	v_mul_hi_i32 v19, v18, s1
	v_lshrrev_b32_e32 v20, 31, v19
	v_ashrrev_i32_e32 v19, 1, v19
	v_add_u32_e32 v30, v19, v20
	v_mad_u64_u32 v[18:19], s[10:11], v30, -12, v[18:19]
	v_add_u32_e32 v20, 0x400, v16
	v_mul_hi_i32 v19, v20, s1
	v_lshrrev_b32_e32 v21, 31, v19
	v_ashrrev_i32_e32 v19, 1, v19
	s_add_u32 s4, s92, 0x36000000
	v_add_u32_e32 v19, v19, v21
	s_addc_u32 s5, s93, 0
	v_mad_u64_u32 v[20:21], s[10:11], v19, -12, v[20:21]
	s_add_u32 s6, s92, 0x3c000000
	v_mul_hi_i32 v21, v16, s1
	s_addc_u32 s7, s93, 0
	v_lshrrev_b32_e32 v22, 31, v21
	v_ashrrev_i32_e32 v21, 1, v21
	s_add_u32 s34, s92, 0x22000000
	v_add_u32_e32 v31, v21, v22
	s_addc_u32 s35, s93, 0
	v_mad_u64_u32 v[22:23], s[10:11], v31, -12, v[16:17]
	s_add_u32 s8, s92, 0x3380000
	v_ashrrev_i32_e32 v24, 4, v16
	s_movk_i32 s11, 0x60
	s_addc_u32 s9, s93, 0
	s_ashr_i32 s10, s0, 1
	v_mad_i64_i32 v[126:127], s[0:1], v31, s11, 0
	v_mad_i64_i32 v[130:131], s[0:1], v30, s11, 0
	v_mad_i64_i32 v[134:135], s[0:1], v19, s11, 0
	v_ashrrev_i32_e32 v25, 31, v24
	v_mov_b32_e32 v125, 0
	v_lshlrev_b64 v[138:139], 12, v[24:25]
	s_mov_b64 s[0:1], 0x20000
	v_and_b32_e32 v124, 32, v17
	v_lshl_add_u64 v[140:141], v[138:139], 0, s[0:1]
	v_lshl_add_u64 v[28:29], s[92:93], 0, v[124:125]
	s_mov_b64 s[0:1], 0x2a00000
	v_lshl_add_u64 v[142:143], v[28:29], 0, s[0:1]
	s_mov_b64 s[0:1], 0x2e00000
	v_lshl_add_u64 v[144:145], v[28:29], 0, s[0:1]
	s_movk_i32 s0, 0x108
	v_lshrrev_b32_e32 v21, 5, v17
	v_lshlrev_b32_e32 v128, 3, v22
	v_mul_lo_u32 v23, v24, s0
	s_movk_i32 s0, 0xd0
	v_ashrrev_i32_e32 v129, 31, v128
	v_lshlrev_b32_e32 v132, 3, v18
	v_lshlrev_b32_e32 v136, 3, v20
	v_lshlrev_b32_e32 v26, 3, v21
	v_lshlrev_b32_e32 v176, 4, v18
	v_lshlrev_b32_e32 v178, 4, v20
	v_mad_u32_u24 v18, v170, s0, 0
	v_mul_u32_u24_e32 v20, 56, v170
	v_lshl_add_u32 v179, v21, 4, v18
	v_add3_u32 v180, v18, v20, v26
	v_lshlrev_b32_e32 v18, 2, v21
	v_lshlrev_b64 v[20:21], 1, v[128:129]
	s_movk_i32 s11, 0xc0
	v_mul_lo_u32 v173, v31, s0
	v_mul_lo_u32 v175, v30, s0
	v_mul_lo_u32 v177, v19, s0
	v_mad_i64_i32 v[20:21], s[0:1], v31, s11, v[20:21]
	v_ashrrev_i32_e32 v133, 31, v132
	v_lshl_add_u64 v[20:21], s[92:93], 0, v[20:21]
	s_mov_b64 s[0:1], 0x36006000
	v_lshl_add_u64 v[148:149], v[20:21], 0, s[0:1]
	v_lshlrev_b64 v[20:21], 1, v[132:133]
	v_mad_i64_i32 v[20:21], s[14:15], v30, s11, v[20:21]
	v_ashrrev_i32_e32 v137, 31, v136
	v_lshl_add_u64 v[20:21], s[92:93], 0, v[20:21]
	v_and_b32_e32 v27, 15, v16
	v_lshl_add_u64 v[150:151], v[20:21], 0, s[0:1]
	v_lshlrev_b64 v[20:21], 1, v[136:137]
	v_lshlrev_b32_e32 v24, 4, v27
	v_mad_i64_i32 v[20:21], s[14:15], v19, s11, v[20:21]
	v_lshlrev_b32_e32 v16, 3, v27
	v_add3_u32 v172, 0, v23, v24
	v_add_u32_e32 v23, 0, v173
	v_lshlrev_b32_e32 v174, 4, v22
	v_add_u32_e32 v22, 0, v175
	v_add_u32_e32 v24, 0, v177
	v_lshl_add_u64 v[20:21], s[92:93], 0, v[20:21]
	s_andn2_b32 s10, s10, 31
	v_add_u32_e32 v181, 0x3400, v179
	v_cmp_gt_u32_e64 s[38:39], 32, v17
	v_lshl_add_u64 v[146:147], s[70:71], 0, v[124:125]
	v_lshl_add_u64 v[152:153], v[20:21], 0, s[0:1]
	v_lshlrev_b32_e32 v124, 1, v16
	v_lshlrev_b32_e32 v154, 1, v26
	v_mov_b32_e32 v182, 0x358637bd
	v_mov_b32_e32 v183, 0x260
	s_mov_b32 s11, 0x3e16c740
	v_add_u32_e32 v184, v23, v174
	v_add_u32_e32 v185, v22, v176
	v_add_u32_e32 v186, v24, v178
	s_mov_b64 s[36:37], 0x6000
	v_lshlrev_b32_e32 v156, 1, v18
	v_mov_b32_e32 v187, 0xc0000
	v_mov_b32_e32 v188, 0x600
	s_mov_b32 s44, s2
	v_and_b32_e32 v249, 31, v166
	v_mul_u32_u24_e32 v249, 0x110, v249
	v_bfe_u32 v251, v166, 5, 1
	v_lshl_add_u32 v249, v251, 4, v249
	v_bfe_u32 v250, v166, 4, 5
	v_mul_u32_u24_e32 v250, 0x110, v250
	v_bfe_u32 v251, v166, 1, 3
	v_lshl_add_u32 v250, v251, 5, v250
	v_and_b32_e32 v251, 1, v166
	v_lshl_add_u32 v250, v251, 3, v250
	v_cmp_gt_u32_e32 vcc, 96, v166
	s_nop 3
	s_and_saveexec_b64 s[0:1], vcc
	v_lshlrev_b32_e32 v251, 2, v166
	global_load_dword v252, v251, s[70:71]
	v_add_u32_e32 v251, 0x1f000, v251
	s_waitcnt vmcnt(0)
	ds_write_b32 v251, v252
	s_mov_b64 exec, s[0:1]
	s_waitcnt lgkmcnt(0)
	s_barrier
	s_branch .LBB0_632

; __device__ __forceinline__ float sq4(f32x4 a) { return (a.x * a.x + a.y * a.y) + (a.z * a.z + a.w * a.w); }
; __device__ __forceinline__ void attn_phase(const Params& p, LAS unsigned char* lds, int G) {
;     ...
;         const int kk = it >> 8, cc = it & 255, bh = cc >> 1, set = cc & 1;
;         const int qt = set ? (14 - 2 * kk + (kk & 1)) : (15 - 2 * kk - (kk & 1));
;         const int q0 = qt * 256 + 32 * wave, lim = q0 >> 6, nkt = 4 * qt + 4;
;         const bf16_t* kbase = KF + (size_t)bh * SEQ * 96; const bf16_t* vbase = VT + (size_t)bh * 64 * SEQ;
;         u32x4 rk0, rk1, rk2, rv0, rv1;
;         ATT_LOAD(0);
;         bf16x8 qf[6];
;         {
;             const size_t qrow = (size_t)(bh >> 3) * SEQ + q0 + l32;
;             const bf16_t* qp = QRAW + qrow * 768 + (bh & 7) * 96 + 8 * hi;
;             u32x4 qr[6];
; #pragma unroll
;             for (int ks = 0; ks < 6; ++ks) qr[ks] = *(const u32x4*)(qp + 16 * ks);
;             const f32x4 c0 = *(const f32x4*)(COS + qrow * 16 + 8 * hi), c1 = *(const f32x4*)(COS + qrow * 16 + 8 * hi + 4);
;             const f32x4 n0 = *(const f32x4*)(SIN + qrow * 16 + 8 * hi), n1 = *(const f32x4*)(SIN + qrow * 16 + 8 * hi + 4);
;             f32x4 xa[6], xb[6]; float ss = 0.f;
; #pragma unroll
;             for (int ks = 0; ks < 6; ++ks) { xa[ks] = (f32x4){bflo(qr[ks].x), bfhi(qr[ks].x), bflo(qr[ks].y), bfhi(qr[ks].y)}; xb[ks] = (f32x4){bflo(qr[ks].z), bfhi(qr[ks].z), bflo(qr[ks].w), bfhi(qr[ks].w)};
;                 ss += sq4(xa[ks]) + sq4(xb[ks]); }
;             ss += __shfl_xor(ss, 32);
.LBB0_636:
	s_bfe_u32 s15, s44, 0x70001
	v_mad_u64_u32 v[160:161], s[0:1], s15, v187, v[148:149]
	v_mad_u64_u32 v[162:163], s[0:1], s15, v187, v[150:151]
	v_mad_u64_u32 v[164:165], s[0:1], s15, v187, v[152:153]
	s_lshl_b32 s0, s14, 8
	s_add_i32 s40, s0, s10
	s_lshl_b32 s49, s14, 2
	s_mul_i32 s0, s15, 0xc0000
	s_add_u32 s0, s4, s0
	s_addc_u32 s1, s5, 0
	v_lshl_add_u64 v[16:17], v[126:127], 1, s[0:1]
	v_lshl_add_u64 v[16:17], v[128:129], 1, v[16:17]
	global_load_dwordx4 v[80:83], v[16:17], off
	v_lshl_add_u64 v[16:17], v[130:131], 1, s[0:1]
	s_lshl_b32 s14, s15, 19
	v_lshl_add_u64 v[16:17], v[132:133], 1, v[16:17]
	s_add_u32 s42, s6, s14
	global_load_dwordx4 v[84:87], v[16:17], off
	v_lshl_add_u64 v[16:17], v[134:135], 1, s[0:1]
	s_addc_u32 s43, s7, 0
	v_lshl_add_u64 v[16:17], v[136:137], 1, v[16:17]
	global_load_dwordx4 v[88:91], v[16:17], off
	v_lshl_add_u64 v[16:17], v[138:139], 1, s[42:43]
	v_lshl_add_u64 v[16:17], v[16:17], 0, v[124:125]
	s_lshl_b32 s0, s44, 8
	global_load_dwordx4 v[92:95], v[16:17], off
	v_lshl_add_u64 v[16:17], v[140:141], 1, s[42:43]
	s_and_b32 s45, s0, 0xf000
	s_ashr_i32 s41, s40, 31
	v_lshl_add_u64 v[16:17], v[16:17], 0, v[124:125]
	s_add_u32 s0, s40, s45
	global_load_dwordx4 v[96:99], v[16:17], off
	v_or_b32_e32 v158, s0, v170
	v_mov_b64_e32 v[16:17], s[34:35]
	s_movk_i32 s0, 0x600
	s_addc_u32 s14, s41, 0
	v_mad_u64_u32 v[16:17], s[0:1], v158, s0, v[16:17]
	s_bfe_u32 s46, s44, 0x30001
	v_mad_i32_i24 v17, s14, v188, v17
	s_mul_i32 s30, s46, 0xc0
	v_lshl_add_u64 v[16:17], v[16:17], 0, s[30:31]
	v_mov_b32_e32 v155, v125
	v_lshl_add_u64 v[16:17], v[16:17], 0, v[154:155]
	global_load_dwordx4 v[44:47], v[16:17], off
	global_load_dwordx4 v[48:51], v[16:17], off offset:32
	global_load_dwordx4 v[52:55], v[16:17], off offset:64
	global_load_dwordx4 v[40:43], v[16:17], off offset:96
	global_load_dwordx4 v[32:35], v[16:17], off offset:128
	global_load_dwordx4 v[36:39], v[16:17], off offset:160
	s_mov_b32 s0, 0xf800000
	v_mov_b32_e32 v159, s14
	v_lshlrev_b64 v[20:21], 6, v[158:159]
	v_lshl_add_u64 v[22:23], v[142:143], 0, v[20:21]
	v_lshl_add_u64 v[28:29], v[144:145], 0, v[20:21]
	global_load_dwordx4 v[16:19], v[22:23], off offset:16
	global_load_dwordx4 v[24:27], v[22:23], off
	s_nop 0
	global_load_dwordx4 v[20:23], v[28:29], off offset:16
	s_nop 0
	global_load_dwordx4 v[28:31], v[28:29], off
	s_add_i32 s49, s49, 4
	s_ashr_i32 s47, s40, 6
	s_mov_b32 s48, 0
	s_lshr_b32 s14, s49, 1
	v_mov_b32_e32 v155, 0
	s_movk_i32 s30, 0x80
	s_mov_b32 s16, 0
	s_waitcnt vmcnt(9)
	v_and_b32_e32 v68, 0xffff0000, v44
	s_waitcnt vmcnt(8)
	v_and_b32_e32 v69, 0xffff0000, v48
	v_and_b32_e32 v73, 0xffff0000, v49
	v_and_b32_e32 v72, 0xffff0000, v45
	v_lshlrev_b32_e32 v67, 16, v48
	v_lshlrev_b32_e32 v66, 16, v44
	v_lshlrev_b32_e32 v71, 16, v49
	v_lshlrev_b32_e32 v70, 16, v45
	v_lshlrev_b32_e32 v106, 16, v46
	v_and_b32_e32 v108, 0xffff0000, v46
	v_lshlrev_b32_e32 v110, 16, v47
	v_and_b32_e32 v112, 0xffff0000, v47
	v_pk_mul_f32 v[44:45], v[68:69], v[68:69]
	v_pk_mul_f32 v[46:47], v[72:73], v[72:73]
	v_and_b32_e32 v109, 0xffff0000, v50
	v_and_b32_e32 v113, 0xffff0000, v51
	v_pk_fma_f32 v[44:45], v[66:67], v[66:67], v[44:45]
	v_pk_fma_f32 v[46:47], v[70:71], v[70:71], v[46:47]
	v_lshlrev_b32_e32 v107, 16, v50
	v_lshlrev_b32_e32 v111, 16, v51
	v_pk_add_f32 v[44:45], v[44:45], v[46:47]
	v_pk_mul_f32 v[46:47], v[108:109], v[108:109]
	v_pk_mul_f32 v[48:49], v[112:113], v[112:113]
	v_pk_fma_f32 v[46:47], v[106:107], v[106:107], v[46:47]
	v_pk_fma_f32 v[48:49], v[110:111], v[110:111], v[48:49]
	s_waitcnt vmcnt(7)
	v_and_b32_e32 v101, 0xffff0000, v54
	v_pk_add_f32 v[46:47], v[46:47], v[48:49]
	v_and_b32_e32 v100, 0xffff0000, v52
	v_and_b32_e32 v105, 0xffff0000, v55
	v_and_b32_e32 v104, 0xffff0000, v53
	v_pk_add_f32 v[48:49], v[44:45], v[46:47]
	v_lshlrev_b32_e32 v79, 16, v54
	v_lshlrev_b32_e32 v78, 16, v52
	v_lshlrev_b32_e32 v103, 16, v55
	v_lshlrev_b32_e32 v102, 16, v53
	v_pk_mul_f32 v[44:45], v[100:101], v[100:101]
	v_pk_mul_f32 v[46:47], v[104:105], v[104:105]
	v_pk_fma_f32 v[44:45], v[78:79], v[78:79], v[44:45]
	v_pk_fma_f32 v[46:47], v[102:103], v[102:103], v[46:47]
	s_waitcnt vmcnt(6)
	v_and_b32_e32 v65, 0xffff0000, v41
	v_and_b32_e32 v64, 0xffff0000, v40
	v_pk_add_f32 v[50:51], v[44:45], v[46:47]
	v_lshlrev_b32_e32 v63, 16, v41
	v_lshlrev_b32_e32 v62, 16, v40
	v_pk_mul_f32 v[40:41], v[64:65], v[64:65]
	v_and_b32_e32 v77, 0xffff0000, v43
	v_and_b32_e32 v76, 0xffff0000, v42
	s_waitcnt vmcnt(4)
	v_lshlrev_b32_e32 v46, 16, v36
	v_pk_fma_f32 v[52:53], v[62:63], v[62:63], v[40:41]
	v_lshlrev_b32_e32 v75, 16, v43
	v_lshlrev_b32_e32 v74, 16, v42
	v_pk_mul_f32 v[40:41], v[76:77], v[76:77]
	v_and_b32_e32 v47, 0xffff0000, v36
	v_lshlrev_b32_e32 v44, 16, v37
	v_and_b32_e32 v45, 0xffff0000, v37
	v_lshlrev_b32_e32 v42, 16, v38
	v_and_b32_e32 v43, 0xffff0000, v38
	v_mul_f32_e32 v38, v46, v46
	v_pk_add_f32 v[36:37], v[48:49], v[48:49] op_sel:[0,1] op_sel_hi:[1,0]
	v_pk_fma_f32 v[54:55], v[74:75], v[74:75], v[40:41]
	v_lshlrev_b32_e32 v40, 16, v39
	v_and_b32_e32 v41, 0xffff0000, v39
	v_mul_f32_e32 v56, v47, v47
	v_mov_b32_e32 v37, v38
	v_pk_add_f32 v[38:39], v[50:51], v[50:51] op_sel:[0,1] op_sel_hi:[1,0]
	v_mul_f32_e32 v57, v44, v44
	v_mov_b32_e32 v39, v56
	v_mul_f32_e32 v114, v45, v45
	v_pk_add_f32 v[36:37], v[36:37], v[38:39]
	v_pk_add_f32 v[38:39], v[52:53], v[52:53] op_sel:[0,1] op_sel_hi:[1,0]
	v_pk_add_f32 v[48:49], v[54:55], v[54:55] op_sel:[0,1] op_sel_hi:[1,0]
	v_mov_b32_e32 v39, v57
	v_mov_b32_e32 v49, v114
	v_and_b32_e32 v59, 0xffff0000, v32
	v_and_b32_e32 v61, 0xffff0000, v33
	v_pk_add_f32 v[38:39], v[38:39], v[48:49]
	v_lshlrev_b32_e32 v58, 16, v32
	v_lshlrev_b32_e32 v60, 16, v33
	v_pk_add_f32 v[36:37], v[36:37], v[38:39]
	v_mul_f32_e32 v38, v59, v59
	v_mul_f32_e32 v48, v61, v61
	v_mul_f32_e32 v115, v42, v42
	v_mul_f32_e32 v116, v43, v43
	v_pk_fma_f32 v[38:39], v[58:59], v[58:59], v[38:39] op_sel_hi:[1,1,0]
	v_pk_fma_f32 v[48:49], v[60:61], v[60:61], v[48:49] op_sel_hi:[1,1,0]
	v_lshlrev_b32_e32 v32, 16, v34
	v_and_b32_e32 v33, 0xffff0000, v34
	v_lshlrev_b32_e32 v34, 16, v35
	v_and_b32_e32 v35, 0xffff0000, v35
	v_mov_b32_e32 v39, v115
	v_mov_b32_e32 v49, v116
	v_pk_add_f32 v[38:39], v[38:39], v[48:49]
	v_mul_f32_e32 v48, v33, v33
	v_mul_f32_e32 v50, v35, v35
	v_mul_f32_e32 v117, v40, v40
	v_mul_f32_e32 v118, v41, v41
	v_pk_fma_f32 v[48:49], v[32:33], v[32:33], v[48:49] op_sel_hi:[1,1,0]
	v_pk_fma_f32 v[50:51], v[34:35], v[34:35], v[50:51] op_sel_hi:[1,1,0]
	v_mov_b32_e32 v49, v117
	v_mov_b32_e32 v51, v118
	v_pk_add_f32 v[48:49], v[48:49], v[50:51]
	v_mov_b32_e32 v54, v66
	v_pk_add_f32 v[38:39], v[38:39], v[48:49]
	v_mov_b32_e32 v55, v68
	v_pk_add_f32 v[36:37], v[36:37], v[38:39]
	v_mov_b32_e32 v68, v67
	v_add_f32_e32 v36, v36, v37
	ds_bpermute_b32 v37, v169, v36
	s_waitcnt lgkmcnt(0)
; __device__ __forceinline__ u32x4 pack8(f32x4 a, f32x4 b) { u32x4 o; o.x = cvt_pk(a.x, a.y); o.y = cvt_pk(a.z, a.w); o.z = cvt_pk(b.x, b.y); o.w = cvt_pk(b.z, b.w); return o; }
; #define LBAR() do { asm volatile("s_waitcnt lgkmcnt(0)" ::: "memory"); __builtin_amdgcn_s_barrier(); asm volatile("" ::: "memory"); } while (0)
; __device__ __forceinline__ void attn_phase(const Params& p, LAS unsigned char* lds, int G) {
;     ...
;             const float r = QSCALE / sqrtf(ss * (1.f / 96.f) + EPS);
; #pragma unroll
;             for (int ks = 0; ks < 6; ++ks) { const f32x4 ga = *(const f32x4*)(p.in[15] + 16 * ks + 8 * hi), gb = *(const f32x4*)(p.in[15] + 16 * ks + 8 * hi + 4);
;                 xa[ks] = xa[ks] * ga * r; xb[ks] = xb[ks] * gb * r; }
;             const f32x4 ra = xa[4] * c0 - xa[5] * n0, rb = xb[4] * c1 - xb[5] * n1, rc = xa[5] * c0 + xa[4] * n0, rd = xb[5] * c1 + xb[4] * n1;
;             xa[4] = ra; xb[4] = rb; xa[5] = rc; xb[5] = rd;
; #pragma unroll
;             for (int ks = 0; ks < 6; ++ks) qf[ks] = __builtin_bit_cast(bf16x8, pack8(xa[ks], xb[ks]));
;         }
;         f32x16 o0, o1;
; #pragma unroll
;         for (int e = 0; e < 16; ++e) { o0[e] = 0.f; o1[e] = 0.f; }
;         float lsum = 0.f;
;         const int nst = nkt >> 1;
;         ATT_STORE(0);
;         LBAR();
	v_add_f32_e32 v36, v36, v37
	v_fmamk_f32 v36, v36, 0x3c2aaaab, v182
	v_cmp_gt_f32_e32 vcc, s0, v36
	v_mul_f32_e32 v37, 0x4f800000, v36
	s_nop 0
	v_cndmask_b32_e32 v36, v36, v37, vcc
	v_sqrt_f32_e32 v37, v36
	s_nop 0
	v_add_u32_e32 v38, -1, v37
	v_fma_f32 v39, -v38, v37, v36
	v_cmp_ge_f32_e64 s[0:1], 0, v39
	v_add_u32_e32 v39, 1, v37
	s_nop 0
	v_cndmask_b32_e64 v38, v37, v38, s[0:1]
	v_fma_f32 v37, -v39, v37, v36
	v_cmp_lt_f32_e64 s[0:1], 0, v37
	s_nop 1
	v_cndmask_b32_e64 v37, v38, v39, s[0:1]
	v_mul_f32_e32 v38, 0x37800000, v37
	v_cndmask_b32_e32 v37, v37, v38, vcc
	v_cmp_class_f32_e32 vcc, v36, v183
	s_nop 1
	v_cndmask_b32_e32 v36, v37, v36, vcc
	v_div_scale_f32 v37, s[0:1], v36, v36, s11
	v_rcp_f32_e32 v38, v37
	s_nop 0
	v_fma_f32 v39, -v37, v38, 1.0
	v_fmac_f32_e32 v38, v39, v38
	v_div_scale_f32 v39, vcc, s11, v36, s11
	v_mul_f32_e32 v48, v39, v38
	v_fma_f32 v49, -v37, v48, v39
	v_fmac_f32_e32 v48, v49, v38
	v_fma_f32 v37, -v37, v48, v39
	v_div_fmas_f32 v37, v37, v38, v48
	v_div_fixup_f32 v48, v37, v36, s11
	v_and_b32_e32 v248, 32, v166
	v_add_u32_e32 v248, 0x1f000, v248
	ds_read_b128 v[36:39], v248 offset:16
	ds_read_b128 v[50:53], v248 offset:0
	s_waitcnt vmcnt(0) lgkmcnt(0)
	v_pk_mul_f32 v[54:55], v[54:55], v[50:51]
	v_mov_b32_e32 v50, v70
	v_mov_b32_e32 v51, v72
	v_pk_mul_f32 v[50:51], v[50:51], v[52:53]
	v_mov_b32_e32 v52, v106
	v_mov_b32_e32 v53, v108
	v_pk_mul_f32 v[36:37], v[52:53], v[36:37]
	v_mov_b32_e32 v52, v110
	v_mov_b32_e32 v53, v112
	v_pk_mul_f32 v[38:39], v[52:53], v[38:39]
	v_pk_mul_f32 v[56:57], v[36:37], v[48:49] op_sel_hi:[1,0]
	v_pk_mul_f32 v[52:53], v[38:39], v[48:49] op_sel_hi:[1,0]
	ds_read_b128 v[36:39], v248 offset:80
	ds_read_b128 v[114:117], v248 offset:64
	v_mov_b32_e32 v108, v107
	v_mov_b32_e32 v112, v111
	v_mov_b32_e32 v72, v71
	v_mov_b32_e32 v110, v78
	v_mov_b32_e32 v111, v100
	v_mov_b32_e32 v100, v79
	v_pk_mul_f32 v[50:51], v[50:51], v[48:49] op_sel_hi:[1,0]
	v_pk_mul_f32 v[54:55], v[54:55], v[48:49] op_sel_hi:[1,0]
	s_waitcnt lgkmcnt(1)
	v_pk_mul_f32 v[36:37], v[108:109], v[36:37]
	s_waitcnt lgkmcnt(0)
	v_pk_mul_f32 v[68:69], v[68:69], v[114:115]
	v_pk_mul_f32 v[38:39], v[112:113], v[38:39]
	v_pk_mul_f32 v[66:67], v[72:73], v[116:117]
	v_pk_mul_f32 v[70:71], v[68:69], v[48:49] op_sel_hi:[1,0]
	v_pk_mul_f32 v[68:69], v[38:39], v[48:49] op_sel_hi:[1,0]
	v_pk_mul_f32 v[72:73], v[36:37], v[48:49] op_sel_hi:[1,0]
	ds_read_b128 v[36:39], v248 offset:144
	ds_read_b128 v[106:109], v248 offset:128
	v_pk_mul_f32 v[66:67], v[66:67], v[48:49] op_sel_hi:[1,0]
	s_waitcnt lgkmcnt(1)
	v_pk_mul_f32 v[36:37], v[100:101], v[36:37]
	s_waitcnt lgkmcnt(0)
	v_pk_mul_f32 v[106:107], v[110:111], v[106:107]
	v_mov_b32_e32 v111, v104
	v_mov_b32_e32 v104, v103
	v_pk_mul_f32 v[38:39], v[104:105], v[38:39]
	v_mov_b32_e32 v110, v102
	v_pk_mul_f32 v[78:79], v[38:39], v[48:49] op_sel_hi:[1,0]
	v_pk_mul_f32 v[112:113], v[36:37], v[48:49] op_sel_hi:[1,0]
	ds_read_b128 v[36:39], v248 offset:208
	ds_read_b128 v[100:103], v248 offset:192
	v_mov_b32_e32 v105, v64
	v_mov_b32_e32 v64, v63
	v_mov_b32_e32 v104, v62
	v_pk_mul_f32 v[108:109], v[110:111], v[108:109]
	s_waitcnt lgkmcnt(0)
	v_pk_mul_f32 v[62:63], v[102:103], v[64:65]
	v_mov_b32_e32 v64, v74
	v_mov_b32_e32 v65, v76
	v_mov_b32_e32 v76, v75
	v_pk_mul_f32 v[100:101], v[100:101], v[104:105]
	v_pk_mul_f32 v[36:37], v[36:37], v[64:65]
	v_pk_mul_f32 v[38:39], v[38:39], v[76:77]
	v_pk_mul_f32 v[114:115], v[100:101], v[48:49] op_sel_hi:[1,0]
	v_pk_mul_f32 v[64:65], v[38:39], v[48:49] op_sel_hi:[1,0]
	v_pk_mul_f32 v[74:75], v[36:37], v[48:49] op_sel_hi:[1,0]
	ds_read_b128 v[36:39], v248 offset:272
	ds_read_b128 v[100:103], v248 offset:256
	v_pk_mul_f32 v[110:111], v[108:109], v[48:49] op_sel_hi:[1,0]
	v_pk_mul_f32 v[108:109], v[106:107], v[48:49] op_sel_hi:[1,0]
	v_pk_mul_f32 v[62:63], v[62:63], v[48:49] op_sel_hi:[1,0]
	s_waitcnt lgkmcnt(1)
	v_pk_mul_f32 v[34:35], v[38:39], v[34:35]
	s_waitcnt lgkmcnt(0)
	v_pk_mul_f32 v[60:61], v[102:103], v[60:61]
	v_pk_mul_f32 v[32:33], v[36:37], v[32:33]
	v_pk_mul_f32 v[58:59], v[100:101], v[58:59]
	v_pk_mul_f32 v[76:77], v[48:49], v[60:61] op_sel_hi:[0,1]
	v_pk_mul_f32 v[60:61], v[48:49], v[32:33] op_sel_hi:[0,1]
	v_pk_mul_f32 v[100:101], v[48:49], v[34:35] op_sel_hi:[0,1]
	ds_read_b128 v[32:35], v248 offset:336
	ds_read_b128 v[36:39], v248 offset:320
	v_pk_mul_f32 v[58:59], v[48:49], v[58:59] op_sel_hi:[0,1]
	s_waitcnt lgkmcnt(1)
	v_pk_mul_f32 v[32:33], v[42:43], v[32:33]
	s_waitcnt lgkmcnt(0)
	v_pk_mul_f32 v[36:37], v[46:47], v[36:37]
	v_pk_mul_f32 v[38:39], v[44:45], v[38:39]
	v_pk_mul_f32 v[34:35], v[40:41], v[34:35]
	v_pk_mul_f32 v[32:33], v[48:49], v[32:33] op_sel_hi:[0,1]
	v_pk_mul_f32 v[38:39], v[48:49], v[38:39] op_sel_hi:[0,1]
	v_pk_mul_f32 v[36:37], v[48:49], v[36:37] op_sel_hi:[0,1]
	v_pk_mul_f32 v[34:35], v[48:49], v[34:35] op_sel_hi:[0,1]
	v_pk_mul_f32 v[44:45], v[20:21], v[32:33]
	v_pk_mul_f32 v[40:41], v[28:29], v[36:37]
	v_pk_mul_f32 v[42:43], v[30:31], v[38:39]
	v_pk_mul_f32 v[46:47], v[22:23], v[34:35]
	v_pk_fma_f32 v[44:45], v[16:17], v[60:61], v[44:45] neg_lo:[0,0,1] neg_hi:[0,0,1]
	v_pk_mul_f32 v[16:17], v[16:17], v[32:33]
	v_pk_fma_f32 v[42:43], v[26:27], v[76:77], v[42:43] neg_lo:[0,0,1] neg_hi:[0,0,1]
	v_pk_fma_f32 v[40:41], v[24:25], v[58:59], v[40:41] neg_lo:[0,0,1] neg_hi:[0,0,1]
	v_pk_fma_f32 v[46:47], v[18:19], v[100:101], v[46:47] neg_lo:[0,0,1] neg_hi:[0,0,1]
	v_pk_mul_f32 v[24:25], v[24:25], v[36:37]
	v_pk_mul_f32 v[26:27], v[26:27], v[38:39]
	v_pk_mul_f32 v[18:19], v[18:19], v[34:35]
	v_pk_fma_f32 v[16:17], v[20:21], v[60:61], v[16:17]
	v_pk_fma_f32 v[26:27], v[30:31], v[76:77], v[26:27]
	v_pk_fma_f32 v[24:25], v[28:29], v[58:59], v[24:25]
	v_pk_fma_f32 v[18:19], v[22:23], v[100:101], v[18:19]
	v_cvt_pk_bf16_f32 v100, v54, v55
	v_cvt_pk_bf16_f32 v101, v50, v51
	v_cvt_pk_bf16_f32 v102, v56, v57
	v_cvt_pk_bf16_f32 v103, v52, v53
	v_cvt_pk_bf16_f32 v104, v70, v71
	v_cvt_pk_bf16_f32 v105, v66, v67
	v_cvt_pk_bf16_f32 v106, v72, v73
	v_cvt_pk_bf16_f32 v107, v68, v69
	v_cvt_pk_bf16_f32 v108, v108, v109
	v_cvt_pk_bf16_f32 v109, v110, v111
	v_cvt_pk_bf16_f32 v110, v112, v113
	v_cvt_pk_bf16_f32 v111, v78, v79
	v_cvt_pk_bf16_f32 v112, v114, v115
	v_cvt_pk_bf16_f32 v113, v62, v63
	v_cvt_pk_bf16_f32 v114, v74, v75
	v_cvt_pk_bf16_f32 v115, v64, v65
	v_cvt_pk_bf16_f32 v116, v40, v41
	v_cvt_pk_bf16_f32 v117, v42, v43
	v_cvt_pk_bf16_f32 v118, v44, v45
	v_cvt_pk_bf16_f32 v119, v46, v47
	v_cvt_pk_bf16_f32 v120, v24, v25
	v_cvt_pk_bf16_f32 v121, v26, v27
	v_cvt_pk_bf16_f32 v122, v16, v17
	v_add_u32_e32 v16, 0xd000, v250
	v_cvt_pk_bf16_f32 v123, v18, v19
	ds_write_b128 v184, v[80:83]
	ds_write_b128 v185, v[84:87]
	ds_write_b128 v186, v[88:91]
	ds_write2_b64 v16, v[92:93], v[94:95] offset1:2
	v_add_u32_e32 v16, 0xf200, v250
	ds_write2_b64 v16, v[96:97], v[98:99] offset1:2
	s_waitcnt lgkmcnt(0)
	s_barrier
; #define LBAR() do { asm volatile("s_waitcnt lgkmcnt(0)" ::: "memory"); __builtin_amdgcn_s_barrier(); asm volatile("" ::: "memory"); } while (0)
; __device__ __forceinline__ void attn_phase(const Params& p, LAS unsigned char* lds, int G) {
;     ...
;         f32x16 o0, o1;
; #pragma unroll
;         for (int e = 0; e < 16; ++e) { o0[e] = 0.f; o1[e] = 0.f; }
;         float lsum = 0.f;
;         const int nst = nkt >> 1;
;         ATT_STORE(0);
;         LBAR();
;         for (int st = 0; st < nst; ++st) {
;             const int buf = st & 1; const bool more = (st + 1 < nst);
;             if (more) ATT_LOAD(st + 1);
;             if (2 * st <= lim) ATT_COMPUTE(buf, 0);
;             if (2 * st + 1 <= lim) ATT_COMPUTE(buf, 1);
;             if (more) ATT_STORE(buf ^ 1);
;             LBAR();
	v_mov_b32_e32 v30, v125
	v_mov_b32_e32 v31, v125
	v_mov_b32_e32 v16, v125
	v_mov_b32_e32 v17, v125
	v_mov_b32_e32 v18, v125
	v_mov_b32_e32 v19, v125
	v_mov_b32_e32 v20, v125
	v_mov_b32_e32 v21, v125
	v_mov_b32_e32 v22, v125
	v_mov_b32_e32 v23, v125
	v_mov_b32_e32 v24, v125
	v_mov_b32_e32 v25, v125
	v_mov_b32_e32 v26, v125
	v_mov_b32_e32 v27, v125
	v_mov_b32_e32 v28, v125
	v_mov_b32_e32 v29, v125
	v_mov_b64_e32 v[46:47], v[30:31]
	v_mov_b64_e32 v[44:45], v[28:29]
	v_mov_b64_e32 v[42:43], v[26:27]
	v_mov_b64_e32 v[40:41], v[24:25]
	v_mov_b64_e32 v[38:39], v[22:23]
	v_mov_b64_e32 v[36:37], v[20:21]
	v_mov_b64_e32 v[34:35], v[18:19]
	v_mov_b64_e32 v[32:33], v[16:17]
	s_mov_b32 s48, 0
	s_lshl_b32 s49, s47, 1
	s_add_u32 s49, s49, 1
	s_mov_b32 s16, 0
	s_mov_b32 s17, 0x15800
	s_mov_b32 s18, 0xd000
	s_mov_b32 s19, 0x11400
	ds_read_b128 v[190:193], v179 offset:0
	ds_read_b128 v[194:197], v179 offset:32
	ds_read_b128 v[198:201], v179 offset:64
	ds_read_b128 v[202:205], v179 offset:96
	ds_read_b128 v[206:209], v179 offset:128
	ds_read_b128 v[210:213], v179 offset:160
	s_lshl_b64 s[0:1], s[30:31], 1
	s_add_u32 s0, s42, s0
	s_addc_u32 s1, s43, s1
	global_load_dwordx4 v[80:83], v[160:161], off
	global_load_dwordx4 v[84:87], v[162:163], off
	global_load_dwordx4 v[88:91], v[164:165], off
	v_lshl_add_u64 v[252:253], v[138:139], 1, s[0:1]
	v_lshl_add_u64 v[252:253], v[252:253], 0, v[124:125]
	global_load_dwordx4 v[92:95], v[252:253], off
	v_lshl_add_u64 v[252:253], v[140:141], 1, s[0:1]
	v_lshl_add_u64 v[252:253], v[252:253], 0, v[124:125]
	global_load_dwordx4 v[96:99], v[252:253], off
	s_addk_i32 s30, 0x80
	v_lshl_add_u64 v[160:161], v[160:161], 0, s[36:37]
	v_lshl_add_u64 v[162:163], v[162:163], 0, s[36:37]
	v_lshl_add_u64 v[164:165], v[164:165], 0, s[36:37]
	v_mov_b32_e32 v238, 0
	v_mov_b32_e32 v239, 0
	v_mov_b32_e32 v240, 0
	v_mov_b32_e32 v241, 0
	v_add_u32_e32 v243, s18, v249
	s_waitcnt lgkmcnt(0)
	v_mfma_f32_32x32x16_bf16 v[48:63], v[190:193], v[100:103], v[0:15]
	v_mfma_f32_32x32x16_bf16 v[48:63], v[194:197], v[104:107], v[48:63]
	v_mfma_f32_32x32x16_bf16 v[48:63], v[198:201], v[108:111], v[48:63]
	v_mfma_f32_32x32x16_bf16 v[48:63], v[202:205], v[112:115], v[48:63]
	v_mfma_f32_32x32x16_bf16 v[48:63], v[206:209], v[116:119], v[48:63]
	v_mfma_f32_32x32x16_bf16 v[48:63], v[210:213], v[120:123], v[48:63]
	ds_read_b128 v[190:193], v179 offset:6656
	ds_read_b128 v[194:197], v179 offset:6688
	ds_read_b128 v[198:201], v179 offset:6720
	ds_read_b128 v[202:205], v179 offset:6752
	ds_read_b128 v[206:209], v179 offset:6784
	ds_read_b128 v[210:213], v179 offset:6816
	ds_read_b128 v[214:217], v243 offset:0
	ds_read_b128 v[218:221], v243 offset:8704
	ds_read_b128 v[222:225], v243 offset:32
	ds_read_b128 v[226:229], v243 offset:8736
	s_nop 7
.Latt_iter:
	v_add_u32_e32 v242, s16, v179
	v_add_u32_e32 v243, s18, v249
	v_add_u32_e32 v244, s17, v249
	s_xor_b32 s0, s16, 0x6800
	v_add_u32_e32 v247, s0, v184
	v_add_u32_e32 v248, s0, v185
	v_add_u32_e32 v251, s0, v186
	v_add_u32_e32 v245, s19, v250
	v_add_u32_e32 v246, 0x2200, v245
	s_cmp_eq_u32 s48, 0
	s_cbranch_scc1 .Latt_skipA
	s_lshl_b32 s15, s48, 2
	s_sub_u32 s15, s15, 1
	s_cmp_le_u32 s15, s49
	s_cbranch_scc0 .Latt_skipA
	s_waitcnt lgkmcnt(9)
	v_mfma_f32_32x32x16_bf16 v[64:79], v[190:193], v[100:103], v[0:15]
	ds_read_b128 v[190:193], v242 offset:0
	v_exp_f32_e32 v48, v48
	v_exp_f32_e32 v49, v49
	v_exp_f32_e32 v50, v50
	s_waitcnt lgkmcnt(9)
	v_mfma_f32_32x32x16_bf16 v[64:79], v[194:197], v[104:107], v[64:79]
	ds_read_b128 v[194:197], v242 offset:32
	v_exp_f32_e32 v51, v51
	v_exp_f32_e32 v52, v52
	v_exp_f32_e32 v53, v53
	s_waitcnt lgkmcnt(9)
	v_mfma_f32_32x32x16_bf16 v[64:79], v[198:201], v[108:111], v[64:79]
	ds_read_b128 v[198:201], v242 offset:64
	v_exp_f32_e32 v54, v54
	v_exp_f32_e32 v55, v55
	v_cvt_pk_bf16_f32 v230, v48, v49
	s_waitcnt lgkmcnt(9)
	v_mfma_f32_32x32x16_bf16 v[64:79], v[202:205], v[112:115], v[64:79]
	ds_read_b128 v[202:205], v242 offset:96
	v_cvt_pk_bf16_f32 v231, v50, v51
	v_exp_f32_e32 v56, v56
	v_exp_f32_e32 v57, v57
	s_waitcnt lgkmcnt(9)
	v_mfma_f32_32x32x16_bf16 v[64:79], v[206:209], v[116:119], v[64:79]
	ds_read_b128 v[206:209], v242 offset:128
	v_cvt_pk_bf16_f32 v232, v52, v53
	v_cvt_pk_bf16_f32 v233, v54, v55
	v_exp_f32_e32 v58, v58
	s_waitcnt lgkmcnt(9)
	v_mfma_f32_32x32x16_bf16 v[64:79], v[210:213], v[120:123], v[64:79]
	ds_read_b128 v[210:213], v242 offset:160
	v_exp_f32_e32 v59, v59
	v_exp_f32_e32 v60, v60
	v_exp_f32_e32 v61, v61
	s_waitcnt lgkmcnt(9)
	v_mfma_f32_32x32x16_bf16 v[16:31], v[214:217], v[230:233], v[16:31]
	ds_read_b128 v[214:217], v244 offset:192
	v_exp_f32_e32 v62, v62
	v_exp_f32_e32 v63, v63
	v_add_f32_e32 v238, v238, v48
	v_add_f32_e32 v239, v239, v49
	s_waitcnt lgkmcnt(9)
	v_mfma_f32_32x32x16_bf16 v[32:47], v[218:221], v[230:233], v[32:47]
	ds_read_b128 v[218:221], v244 offset:8896
	v_cvt_pk_bf16_f32 v234, v56, v57
	v_cvt_pk_bf16_f32 v235, v58, v59
	v_cvt_pk_bf16_f32 v236, v60, v61
	v_cvt_pk_bf16_f32 v237, v62, v63
	v_add_f32_e32 v240, v240, v50
	v_add_f32_e32 v241, v241, v51
	s_waitcnt lgkmcnt(9)
	v_mfma_f32_32x32x16_bf16 v[16:31], v[222:225], v[234:237], v[16:31]
	ds_read_b128 v[222:225], v244 offset:224
	v_add_f32_e32 v238, v238, v52
	v_add_f32_e32 v239, v239, v53
	v_add_f32_e32 v240, v240, v54
	v_add_f32_e32 v241, v241, v55
	v_add_f32_e32 v238, v238, v56
	v_add_f32_e32 v239, v239, v57
	s_waitcnt lgkmcnt(9)
	v_mfma_f32_32x32x16_bf16 v[32:47], v[226:229], v[234:237], v[32:47]
	ds_read_b128 v[226:229], v244 offset:8928
	v_add_f32_e32 v240, v240, v58
	v_add_f32_e32 v241, v241, v59
	v_add_f32_e32 v238, v238, v60
	v_add_f32_e32 v239, v239, v61
	v_add_f32_e32 v240, v240, v62
	v_add_f32_e32 v241, v241, v63
	s_waitcnt lgkmcnt(9)
	v_mfma_f32_32x32x16_bf16 v[48:63], v[190:193], v[100:103], v[0:15]
	ds_read_b128 v[190:193], v242 offset:6656
	v_exp_f32_e32 v64, v64
	v_exp_f32_e32 v65, v65
	v_exp_f32_e32 v66, v66
	s_waitcnt lgkmcnt(9)
	v_mfma_f32_32x32x16_bf16 v[48:63], v[194:197], v[104:107], v[48:63]
	ds_read_b128 v[194:197], v242 offset:6688
	v_exp_f32_e32 v67, v67
	v_exp_f32_e32 v68, v68
	v_exp_f32_e32 v69, v69
	s_waitcnt lgkmcnt(9)
	v_mfma_f32_32x32x16_bf16 v[48:63], v[198:201], v[108:111], v[48:63]
	ds_read_b128 v[198:201], v242 offset:6720
	v_exp_f32_e32 v70, v70
	v_exp_f32_e32 v71, v71
	v_cvt_pk_bf16_f32 v230, v64, v65
	s_waitcnt lgkmcnt(9)
	v_mfma_f32_32x32x16_bf16 v[48:63], v[202:205], v[112:115], v[48:63]
	ds_read_b128 v[202:205], v242 offset:6752
	v_cvt_pk_bf16_f32 v231, v66, v67
	v_exp_f32_e32 v72, v72
	v_exp_f32_e32 v73, v73
	s_waitcnt lgkmcnt(9)
	v_mfma_f32_32x32x16_bf16 v[48:63], v[206:209], v[116:119], v[48:63]
	ds_read_b128 v[206:209], v242 offset:6784
	v_cvt_pk_bf16_f32 v232, v68, v69
	v_cvt_pk_bf16_f32 v233, v70, v71
	v_exp_f32_e32 v74, v74
	s_waitcnt lgkmcnt(9)
	v_mfma_f32_32x32x16_bf16 v[48:63], v[210:213], v[120:123], v[48:63]
	ds_read_b128 v[210:213], v242 offset:6816
	v_exp_f32_e32 v75, v75
	v_exp_f32_e32 v76, v76
	v_exp_f32_e32 v77, v77
	s_waitcnt lgkmcnt(9)
	v_mfma_f32_32x32x16_bf16 v[16:31], v[214:217], v[230:233], v[16:31]
	ds_read_b128 v[214:217], v243 offset:0
	v_exp_f32_e32 v78, v78
	v_exp_f32_e32 v79, v79
	v_add_f32_e32 v238, v238, v64
	v_add_f32_e32 v239, v239, v65
	s_waitcnt lgkmcnt(9)
	v_mfma_f32_32x32x16_bf16 v[32:47], v[218:221], v[230:233], v[32:47]
	ds_read_b128 v[218:221], v243 offset:8704
	v_cvt_pk_bf16_f32 v234, v72, v73
	v_cvt_pk_bf16_f32 v235, v74, v75
	v_cvt_pk_bf16_f32 v236, v76, v77
	v_cvt_pk_bf16_f32 v237, v78, v79
	v_add_f32_e32 v240, v240, v66
	v_add_f32_e32 v241, v241, v67
	s_waitcnt lgkmcnt(9)
	v_mfma_f32_32x32x16_bf16 v[16:31], v[222:225], v[234:237], v[16:31]
	ds_read_b128 v[222:225], v243 offset:32
	v_add_f32_e32 v238, v238, v68
	v_add_f32_e32 v239, v239, v69
	v_add_f32_e32 v240, v240, v70
	v_add_f32_e32 v241, v241, v71
	v_add_f32_e32 v238, v238, v72
	v_add_f32_e32 v239, v239, v73
	s_waitcnt lgkmcnt(9)
	v_mfma_f32_32x32x16_bf16 v[32:47], v[226:229], v[234:237], v[32:47]
	ds_read_b128 v[226:229], v243 offset:8736
	v_add_f32_e32 v240, v240, v74
	v_add_f32_e32 v241, v241, v75
	v_add_f32_e32 v238, v238, v76
	v_add_f32_e32 v239, v239, v77
	v_add_f32_e32 v240, v240, v78
	v_add_f32_e32 v241, v241, v79
.Latt_skipA:
	s_lshl_b32 s15, s48, 2
	s_add_u32 s15, s15, 1
	s_cmp_le_u32 s15, s49
	s_cbranch_scc0 .Latt_skipB
	s_waitcnt lgkmcnt(9)
	v_mfma_f32_32x32x16_bf16 v[64:79], v[190:193], v[100:103], v[0:15]
	ds_read_b128 v[190:193], v242 offset:13312
	v_exp_f32_e32 v48, v48
	v_exp_f32_e32 v49, v49
	v_exp_f32_e32 v50, v50
	s_waitcnt lgkmcnt(9)
	v_mfma_f32_32x32x16_bf16 v[64:79], v[194:197], v[104:107], v[64:79]
	ds_read_b128 v[194:197], v242 offset:13344
	v_exp_f32_e32 v51, v51
	v_exp_f32_e32 v52, v52
	v_exp_f32_e32 v53, v53
	s_waitcnt lgkmcnt(9)
	v_mfma_f32_32x32x16_bf16 v[64:79], v[198:201], v[108:111], v[64:79]
	ds_read_b128 v[198:201], v242 offset:13376
	v_exp_f32_e32 v54, v54
	v_exp_f32_e32 v55, v55
	v_cvt_pk_bf16_f32 v230, v48, v49
	s_waitcnt lgkmcnt(9)
	v_mfma_f32_32x32x16_bf16 v[64:79], v[202:205], v[112:115], v[64:79]
	ds_read_b128 v[202:205], v242 offset:13408
	v_cvt_pk_bf16_f32 v231, v50, v51
	v_exp_f32_e32 v56, v56
	v_exp_f32_e32 v57, v57
	s_waitcnt lgkmcnt(9)
	v_mfma_f32_32x32x16_bf16 v[64:79], v[206:209], v[116:119], v[64:79]
	ds_read_b128 v[206:209], v242 offset:13440
	v_cvt_pk_bf16_f32 v232, v52, v53
	v_cvt_pk_bf16_f32 v233, v54, v55
	v_exp_f32_e32 v58, v58
	s_waitcnt lgkmcnt(9)
	v_mfma_f32_32x32x16_bf16 v[64:79], v[210:213], v[120:123], v[64:79]
	ds_read_b128 v[210:213], v242 offset:13472
	v_exp_f32_e32 v59, v59
	v_exp_f32_e32 v60, v60
	v_exp_f32_e32 v61, v61
	s_waitcnt lgkmcnt(9)
	v_mfma_f32_32x32x16_bf16 v[16:31], v[214:217], v[230:233], v[16:31]
	ds_read_b128 v[214:217], v243 offset:64
	v_exp_f32_e32 v62, v62
	v_exp_f32_e32 v63, v63
	v_add_f32_e32 v238, v238, v48
	v_add_f32_e32 v239, v239, v49
	s_waitcnt lgkmcnt(9)
	v_mfma_f32_32x32x16_bf16 v[32:47], v[218:221], v[230:233], v[32:47]
	ds_read_b128 v[218:221], v243 offset:8768
	v_cvt_pk_bf16_f32 v234, v56, v57
	v_cvt_pk_bf16_f32 v235, v58, v59
	v_cvt_pk_bf16_f32 v236, v60, v61
	v_cvt_pk_bf16_f32 v237, v62, v63
	v_add_f32_e32 v240, v240, v50
	v_add_f32_e32 v241, v241, v51
	s_waitcnt lgkmcnt(9)
	v_mfma_f32_32x32x16_bf16 v[16:31], v[222:225], v[234:237], v[16:31]
	ds_read_b128 v[222:225], v243 offset:96
	v_add_f32_e32 v238, v238, v52
	v_add_f32_e32 v239, v239, v53
	v_add_f32_e32 v240, v240, v54
	v_add_f32_e32 v241, v241, v55
	v_add_f32_e32 v238, v238, v56
	v_add_f32_e32 v239, v239, v57
	s_waitcnt lgkmcnt(9)
	v_mfma_f32_32x32x16_bf16 v[32:47], v[226:229], v[234:237], v[32:47]
	ds_read_b128 v[226:229], v243 offset:8800
	v_add_f32_e32 v240, v240, v58
	v_add_f32_e32 v241, v241, v59
	v_add_f32_e32 v238, v238, v60
	v_add_f32_e32 v239, v239, v61
	v_add_f32_e32 v240, v240, v62
	v_add_f32_e32 v241, v241, v63
	s_add_u32 s15, s48, 2
	s_cmp_lt_u32 s15, s14
	s_cbranch_scc0 .Latt_b1plain
; #define LBAR() do { asm volatile("s_waitcnt lgkmcnt(0)" ::: "memory"); __builtin_amdgcn_s_barrier(); asm volatile("" ::: "memory"); } while (0)
; __device__ __forceinline__ void attn_phase(const Params& p, LAS unsigned char* lds, int G) {
;     ...
;         for (int st = 0; st < nst; ++st) {
;             const int buf = st & 1; const bool more = (st + 1 < nst);
;             if (more) ATT_LOAD(st + 1);
;             if (2 * st <= lim) ATT_COMPUTE(buf, 0);
;             if (2 * st + 1 <= lim) ATT_COMPUTE(buf, 1);
;             if (more) ATT_STORE(buf ^ 1);
;             LBAR();
;         }
	s_lshl_b64 s[0:1], s[30:31], 1
	s_add_u32 s0, s42, s0
	s_addc_u32 s1, s43, s1
	s_waitcnt lgkmcnt(7)
	v_mfma_f32_32x32x16_bf16 v[48:63], v[190:193], v[100:103], v[0:15]
	v_exp_f32_e32 v64, v64
	v_exp_f32_e32 v65, v65
	v_exp_f32_e32 v66, v66
	s_waitcnt vmcnt(0)
	ds_write_b128 v247, v[80:83]
	v_mfma_f32_32x32x16_bf16 v[48:63], v[194:197], v[104:107], v[48:63]
	v_exp_f32_e32 v67, v67
	v_exp_f32_e32 v68, v68
	v_exp_f32_e32 v69, v69
	ds_write_b128 v248, v[84:87]
	v_mfma_f32_32x32x16_bf16 v[48:63], v[198:201], v[108:111], v[48:63]
	ds_read_b128 v[190:193], v242 offset:19968
	ds_read_b128 v[194:197], v242 offset:20000
	ds_read_b128 v[198:201], v242 offset:20032
	v_exp_f32_e32 v70, v70
	v_exp_f32_e32 v71, v71
	v_cvt_pk_bf16_f32 v230, v64, v65
	v_cvt_pk_bf16_f32 v231, v66, v67
	ds_write_b128 v251, v[88:91]
	s_waitcnt lgkmcnt(10)
	v_mfma_f32_32x32x16_bf16 v[48:63], v[202:205], v[112:115], v[48:63]
	v_cvt_pk_bf16_f32 v232, v68, v69
	v_cvt_pk_bf16_f32 v233, v70, v71
	v_exp_f32_e32 v72, v72
	v_exp_f32_e32 v73, v73
	ds_write2_b64 v245, v[92:93], v[94:95] offset1:2
	v_mfma_f32_32x32x16_bf16 v[48:63], v[206:209], v[116:119], v[48:63]
	v_exp_f32_e32 v74, v74
	v_exp_f32_e32 v75, v75
	v_exp_f32_e32 v76, v76
	ds_write2_b64 v246, v[96:97], v[98:99] offset1:2
	v_mfma_f32_32x32x16_bf16 v[48:63], v[210:213], v[120:123], v[48:63]
	ds_read_b128 v[202:205], v242 offset:20064
	ds_read_b128 v[206:209], v242 offset:20096
	ds_read_b128 v[210:213], v242 offset:20128
	v_exp_f32_e32 v77, v77
	v_exp_f32_e32 v78, v78
	v_exp_f32_e32 v79, v79
	global_load_dwordx4 v[80:83], v[160:161], off
	s_waitcnt lgkmcnt(11)
	v_mfma_f32_32x32x16_bf16 v[16:31], v[214:217], v[230:233], v[16:31]
	v_cvt_pk_bf16_f32 v234, v72, v73
	v_cvt_pk_bf16_f32 v235, v74, v75
	v_cvt_pk_bf16_f32 v236, v76, v77
	v_cvt_pk_bf16_f32 v237, v78, v79
	v_add_f32_e32 v238, v238, v64
	v_add_f32_e32 v239, v239, v65
	global_load_dwordx4 v[84:87], v[162:163], off
	v_mfma_f32_32x32x16_bf16 v[32:47], v[218:221], v[230:233], v[32:47]
	v_add_f32_e32 v240, v240, v66
	v_add_f32_e32 v241, v241, v67
	v_add_f32_e32 v238, v238, v68
	v_add_f32_e32 v239, v239, v69
	v_add_f32_e32 v240, v240, v70
	v_add_f32_e32 v241, v241, v71
	global_load_dwordx4 v[88:91], v[164:165], off
	v_lshl_add_u64 v[252:253], v[138:139], 1, s[0:1]
	v_lshl_add_u64 v[252:253], v[252:253], 0, v[124:125]
	v_mfma_f32_32x32x16_bf16 v[16:31], v[222:225], v[234:237], v[16:31]
	v_add_f32_e32 v238, v238, v72
	v_add_f32_e32 v239, v239, v73
	v_add_f32_e32 v240, v240, v74
	v_add_f32_e32 v241, v241, v75
	v_add_f32_e32 v238, v238, v76
	v_add_f32_e32 v239, v239, v77
	global_load_dwordx4 v[92:95], v[252:253], off
	v_lshl_add_u64 v[252:253], v[140:141], 1, s[0:1]
	v_lshl_add_u64 v[252:253], v[252:253], 0, v[124:125]
	v_mfma_f32_32x32x16_bf16 v[32:47], v[226:229], v[234:237], v[32:47]
	ds_read_b128 v[214:217], v243 offset:128
	ds_read_b128 v[218:221], v243 offset:8832
	ds_read_b128 v[222:225], v243 offset:160
	ds_read_b128 v[226:229], v243 offset:8864
	v_add_f32_e32 v240, v240, v78
	v_add_f32_e32 v241, v241, v79
	global_load_dwordx4 v[96:99], v[252:253], off
	s_addk_i32 s30, 0x80
	v_lshl_add_u64 v[160:161], v[160:161], 0, s[36:37]
	v_lshl_add_u64 v[162:163], v[162:163], 0, s[36:37]
	v_lshl_add_u64 v[164:165], v[164:165], 0, s[36:37]
	s_branch .Latt_skipB
.Latt_b1plain:
	s_waitcnt lgkmcnt(9)
	v_mfma_f32_32x32x16_bf16 v[48:63], v[190:193], v[100:103], v[0:15]
	ds_read_b128 v[190:193], v242 offset:19968
	v_exp_f32_e32 v64, v64
	v_exp_f32_e32 v65, v65
	v_exp_f32_e32 v66, v66
	s_waitcnt lgkmcnt(9)
	v_mfma_f32_32x32x16_bf16 v[48:63], v[194:197], v[104:107], v[48:63]
	ds_read_b128 v[194:197], v242 offset:20000
	v_exp_f32_e32 v67, v67
	v_exp_f32_e32 v68, v68
	v_exp_f32_e32 v69, v69
	s_waitcnt lgkmcnt(9)
	v_mfma_f32_32x32x16_bf16 v[48:63], v[198:201], v[108:111], v[48:63]
	ds_read_b128 v[198:201], v242 offset:20032
	v_exp_f32_e32 v70, v70
	v_exp_f32_e32 v71, v71
	v_cvt_pk_bf16_f32 v230, v64, v65
	s_waitcnt lgkmcnt(9)
	v_mfma_f32_32x32x16_bf16 v[48:63], v[202:205], v[112:115], v[48:63]
	ds_read_b128 v[202:205], v242 offset:20064
	v_cvt_pk_bf16_f32 v231, v66, v67
	v_exp_f32_e32 v72, v72
	v_exp_f32_e32 v73, v73
	s_waitcnt lgkmcnt(9)
	v_mfma_f32_32x32x16_bf16 v[48:63], v[206:209], v[116:119], v[48:63]
	ds_read_b128 v[206:209], v242 offset:20096
	v_cvt_pk_bf16_f32 v232, v68, v69
	v_cvt_pk_bf16_f32 v233, v70, v71
	v_exp_f32_e32 v74, v74
	s_waitcnt lgkmcnt(9)
	v_mfma_f32_32x32x16_bf16 v[48:63], v[210:213], v[120:123], v[48:63]
	ds_read_b128 v[210:213], v242 offset:20128
	v_exp_f32_e32 v75, v75
	v_exp_f32_e32 v76, v76
	v_exp_f32_e32 v77, v77
	s_waitcnt lgkmcnt(9)
	v_mfma_f32_32x32x16_bf16 v[16:31], v[214:217], v[230:233], v[16:31]
	ds_read_b128 v[214:217], v243 offset:128
	v_exp_f32_e32 v78, v78
	v_exp_f32_e32 v79, v79
	v_add_f32_e32 v238, v238, v64
	v_add_f32_e32 v239, v239, v65
	s_waitcnt lgkmcnt(9)
	v_mfma_f32_32x32x16_bf16 v[32:47], v[218:221], v[230:233], v[32:47]
	ds_read_b128 v[218:221], v243 offset:8832
	v_cvt_pk_bf16_f32 v234, v72, v73
	v_cvt_pk_bf16_f32 v235, v74, v75
	v_cvt_pk_bf16_f32 v236, v76, v77
	v_cvt_pk_bf16_f32 v237, v78, v79
	v_add_f32_e32 v240, v240, v66
	v_add_f32_e32 v241, v241, v67
	s_waitcnt lgkmcnt(9)
	v_mfma_f32_32x32x16_bf16 v[16:31], v[222:225], v[234:237], v[16:31]
	ds_read_b128 v[222:225], v243 offset:160
	v_add_f32_e32 v238, v238, v68
	v_add_f32_e32 v239, v239, v69
	v_add_f32_e32 v240, v240, v70
	v_add_f32_e32 v241, v241, v71
	v_add_f32_e32 v238, v238, v72
	v_add_f32_e32 v239, v239, v73
	s_waitcnt lgkmcnt(9)
	v_mfma_f32_32x32x16_bf16 v[32:47], v[226:229], v[234:237], v[32:47]
	ds_read_b128 v[226:229], v243 offset:8864
	v_add_f32_e32 v240, v240, v74
	v_add_f32_e32 v241, v241, v75
	v_add_f32_e32 v238, v238, v76
	v_add_f32_e32 v239, v239, v77
	v_add_f32_e32 v240, v240, v78
	v_add_f32_e32 v241, v241, v79
.Latt_skipB:
	s_add_u32 s15, s48, 2
	s_cmp_eq_u32 s15, s14
	s_cbranch_scc0 .Latt_nostore
	s_waitcnt vmcnt(0)
	ds_write_b128 v247, v[80:83]
	ds_write_b128 v248, v[84:87]
	ds_write_b128 v251, v[88:91]
	ds_write2_b64 v245, v[92:93], v[94:95] offset1:2
	ds_write2_b64 v246, v[96:97], v[98:99] offset1:2
